# v006 + attention K LDS image swizzle chunk^(row&15) instead of chunk^swz(row) (conflict-free for the documented ds_read_b128 lane groups)
# baseline (speedup 1.0000x reference)
; #define LAS __attribute__((address_space(3)))
; __device__ __forceinline__ unsigned swz(unsigned row) { return ((row & 3u) << 2) | ((row >> 2) & 3u); }
; __device__ __forceinline__ void segment(LAS unsigned char* lds, const bf16* __restrict__ QKV, bf16* __restrict__ Og, float* __restrict__ L2, int bl, int g, int h, int r, int dil, int n0, int cnt, int tid) {
;     const int lane = tid & 63, w = __builtin_amdgcn_readfirstlane(tid >> 6), lq = lane & 15, gq = lane >> 4;
;     const size_t rowbase = (size_t)bl * SEQ + r;
;     const bf16* qcol = QKV + (size_t)g * 3072 + h * 128;
;     const int srow = tid >> 4, sch = tid & 15;
;     const unsigned sdst = 256u * srow + 16u * ((unsigned)sch ^ swz(srow));
;     const unsigned sdstv = VBASE + 256u * srow + 16u * ((unsigned)sch ^ (2u * (srow & 7)));
;     unsigned koff[4], voff[8];
; #pragma unroll
;     for (int s = 0; s < 4; ++s) koff[s] = 256u * lq + 16u * ((unsigned)(4 * s + gq) ^ swz(lq));
;     { const unsigned q4 = lq >> 2, p4 = lq & 3, rowv = 4 * gq + q4;
; #pragma unroll
;       for (int c = 0; c < 8; ++c) voff[c] = 256u * rowv + 16u * ((unsigned)(2 * c + (p4 & 1)) ^ (2u * (rowv & 7))) + 8u * (p4 >> 1); }
;     const float cb = exp2f(-8.0f * (float)(g * 8 + h + 1) / 24.0f) * (float)dil * 1.4426950408889634f;
;     const float basel = -cb * (float)(128 + lq - 4 * gq);
.LBB0_276:
	s_cmp_lt_i32 s84, 3
	s_cselect_b64 s[4:5], -1, 0
	s_add_u32 s2, s82, 0x200000
	s_addc_u32 s3, s83, 0
	v_writelane_b32 v239, s2, 51
	s_and_b64 s[0:1], s[4:5], s[0:1]
	s_andn2_b64 vcc, exec, s[0:1]
	v_writelane_b32 v239, s3, 52
	v_writelane_b32 v239, s80, 53
	s_nop 1
	v_writelane_b32 v239, s81, 54
	v_writelane_b32 v239, s82, 55
	v_writelane_b32 v239, s83, 56
	v_writelane_b32 v239, s84, 57
	v_writelane_b32 v239, s85, 58
	v_writelane_b32 v239, s86, 59
	v_writelane_b32 v239, s87, 60
	s_cbranch_vccnz .LBB0_302
	v_writelane_b32 v239, s4, 61
	s_nop 1
	v_writelane_b32 v239, s5, 62
	s_nop 0
	v_readlane_b32 s0, v239, 0
	s_cmpk_gt_i32 s0, 0x2ff
	s_cbranch_scc1 .LBB0_301
	v_lshlrev_b32_e32 v5, 2, v154
	v_and_b32_e32 v119, 15, v154
	v_bfe_u32 v1, v154, 4, 2
	v_and_b32_e32 v6, 12, v5
	v_bfe_u32 v7, v154, 2, 2
	v_lshrrev_b32_e32 v2, 2, v154
	v_lshlrev_b32_e32 v4, 8, v119
	v_or_b32_e32 v8, v6, v7
	v_bitop3_b32 v6, v6, v1, v7 bitop3:0x36
	v_lshrrev_b32_e32 v122, 4, v154
	v_and_b32_e32 v2, 12, v2
	v_bfe_u32 v3, v154, 6, 2
	v_lshl_or_b32 v123, v6, 4, v4
	v_bitop3_b32 v6, v1, v8, 4 bitop3:0x36
	v_lshlrev_b32_e32 v0, 8, v122
	v_bitop3_b32 v2, v2, v119, v3 bitop3:0x36
	v_lshl_or_b32 v124, v6, 4, v4
	v_bitop3_b32 v6, v1, v8, 8 bitop3:0x36
	v_lshl_or_b32 v125, v6, 4, v4
	v_bitop3_b32 v6, v1, v8, 12 bitop3:0x36
	v_lshl_or_b32 v127, v2, 4, v0
	v_lshlrev_b32_e32 v2, 2, v1
	v_lshl_or_b32 v126, v6, 4, v4
	v_xor_b32_e32 v6, v1, v119
	v_lshl_or_b32 v123, v6, 4, v4
	v_or_b32_e32 v6, 4, v1
	v_xor_b32_e32 v6, v6, v119
	v_lshl_or_b32 v124, v6, 4, v4
	v_or_b32_e32 v6, 8, v1
	v_xor_b32_e32 v6, v6, v119
	v_lshl_or_b32 v125, v6, 4, v4
	v_or_b32_e32 v6, 12, v1
	v_xor_b32_e32 v6, v6, v119
	v_lshl_or_b32 v126, v6, 4, v4
	v_and_b32_e32 v6, 15, v122
	v_xor_b32_e32 v6, v6, v119
	v_lshl_or_b32 v127, v6, 4, v0
	v_or_b32_e32 v4, v2, v7
	v_lshlrev_b32_e32 v7, 1, v4
	v_and_b32_e32 v6, 1, v154
	v_and_b32_e32 v8, 14, v7
	v_and_b32_e32 v5, 8, v5
	v_lshl_or_b32 v4, v4, 8, v5
	v_or_b32_e32 v5, v8, v6
	v_lshl_or_b32 v128, v5, 4, v4
	v_or_b32_e32 v5, 2, v6
	v_bitop3_b32 v5, v7, v5, 14 bitop3:0x6c
	v_lshl_or_b32 v129, v5, 4, v4
	v_or_b32_e32 v5, 4, v6
	v_bitop3_b32 v5, v7, v5, 14 bitop3:0x6c
	v_lshrrev_b32_e32 v3, 3, v154
	v_lshl_or_b32 v130, v5, 4, v4
	v_or_b32_e32 v5, 6, v6
	v_bitop3_b32 v3, v3, v119, 14 bitop3:0x6c
	v_bitop3_b32 v5, v7, v5, 14 bitop3:0x6c
	v_lshlrev_b32_e32 v3, 4, v3
	v_lshl_or_b32 v131, v5, 4, v4
	v_or_b32_e32 v5, 8, v6
	s_mov_b32 s0, 0x10000
	v_bitop3_b32 v5, v7, v5, 14 bitop3:0x6c
	v_or3_b32 v136, v3, v0, s0
	v_or_b32_e32 v0, 0x80, v119
	v_lshl_or_b32 v132, v5, 4, v4
	v_or_b32_e32 v5, 10, v6
	v_sub_u32_e32 v0, v0, v2
	v_bitop3_b32 v5, v7, v5, 14 bitop3:0x6c
	v_cvt_f32_ubyte0_e32 v137, v0
	v_or_b32_e32 v0, 1, v2
	v_lshl_or_b32 v133, v5, 4, v4
	v_or_b32_e32 v5, 12, v6
	v_cmp_ge_u32_e64 s[4:5], v2, v119
	v_cmp_ge_u32_e64 s[6:7], v0, v119
	v_or_b32_e32 v0, 2, v2
	v_or_b32_e32 v3, 3, v2
	v_cmp_gt_u32_e64 s[12:13], v2, v119
	v_cmp_lt_u32_e64 s[14:15], v2, v119
	v_mbcnt_lo_u32_b32 v2, -1, 0
	v_bitop3_b32 v5, v7, v5, 14 bitop3:0x6c
	v_mbcnt_hi_u32_b32 v2, -1, v2
	v_lshl_or_b32 v134, v5, 4, v4
	v_bitop3_b32 v5, v7, v6, 14 bitop3:0x4e
	v_and_b32_e32 v6, 64, v2
	v_lshl_or_b32 v135, v5, 4, v4
	v_xor_b32_e32 v5, 16, v2
	v_add_u32_e32 v6, 64, v6
	v_cmp_lt_i32_e32 vcc, v5, v6
	v_cmp_ge_u32_e64 s[10:11], v3, v119
	v_cmp_gt_u32_e64 s[18:19], v3, v119
	v_cndmask_b32_e32 v5, v2, v5, vcc
	v_lshlrev_b32_e32 v139, 2, v5
	v_xor_b32_e32 v5, 32, v2
	v_cmp_lt_i32_e32 vcc, v5, v6
	v_mov_b32_e32 v3, 0
	s_mov_b64 s[0:1], 0x7c00000
	v_cndmask_b32_e32 v2, v2, v5, vcc
	v_lshlrev_b32_e32 v140, 2, v2
	v_lshlrev_b32_e32 v2, 4, v1
	v_lshl_add_u64 v[6:7], s[82:83], 0, v[2:3]
	v_cmp_ge_u32_e64 s[8:9], v0, v119
	v_cmp_gt_u32_e64 s[16:17], v0, v119
	v_lshlrev_b32_e32 v0, 3, v119
	v_lshlrev_b32_e32 v4, 3, v1
	v_lshl_add_u64 v[68:69], s[80:81], 0, v[2:3]
	v_lshl_add_u64 v[70:71], v[6:7], 0, s[0:1]
	v_lshlrev_b32_e32 v2, 4, v119
	v_readlane_b32 s0, v239, 0
	v_or_b32_e32 v138, 0xffffff80, v122
	s_mov_b32 s41, 0
	v_cmp_eq_u32_e64 s[2:3], 0, v1
	v_lshl_add_u64 v[72:73], s[82:83], 0, v[2:3]
	v_mov_b32_e32 v141, 0x42800000
	v_lshlrev_b32_e32 v74, 1, v4
	v_mov_b32_e32 v75, v3
	v_lshlrev_b32_e32 v76, 1, v0
	v_mov_b32_e32 v77, v3
	v_mov_b64_e32 v[78:79], 0x2d0000
	v_mov_b64_e32 v[80:81], 0x240000
	v_mov_b64_e32 v[82:83], 0x360000
	v_mov_b64_e32 v[84:85], 0x3f0000
	v_mov_b32_e32 v142, 0xff800000
	s_mov_b32 s25, s0
	v_writelane_b32 v239, s64, 63
	s_nop 1
	v_writelane_b32 v238, s65, 0
	s_branch .LBB0_280

; #define LAS __attribute__((address_space(3)))
; __device__ __forceinline__ unsigned swz(unsigned row) { return ((row & 3u) << 2) | ((row >> 2) & 3u); }
; __device__ __forceinline__ void segment(LAS unsigned char* lds, const bf16* __restrict__ QKV, bf16* __restrict__ Og, float* __restrict__ L2, int bl, int g, int h, int r, int dil, int n0, int cnt, int tid) {
;     const int lane = tid & 63, w = __builtin_amdgcn_readfirstlane(tid >> 6), lq = lane & 15, gq = lane >> 4;
;     const size_t rowbase = (size_t)bl * SEQ + r;
;     const bf16* qcol = QKV + (size_t)g * 3072 + h * 128;
;     const int srow = tid >> 4, sch = tid & 15;
;     const unsigned sdst = 256u * srow + 16u * ((unsigned)sch ^ swz(srow));
;     const unsigned sdstv = VBASE + 256u * srow + 16u * ((unsigned)sch ^ (2u * (srow & 7)));
;     unsigned koff[4], voff[8];
; #pragma unroll
;     for (int s = 0; s < 4; ++s) koff[s] = 256u * lq + 16u * ((unsigned)(4 * s + gq) ^ swz(lq));
;     { const unsigned q4 = lq >> 2, p4 = lq & 3, rowv = 4 * gq + q4;
; #pragma unroll
;       for (int c = 0; c < 8; ++c) voff[c] = 256u * rowv + 16u * ((unsigned)(2 * c + (p4 & 1)) ^ (2u * (rowv & 7))) + 8u * (p4 >> 1); }
;     const float cb = exp2f(-8.0f * (float)(g * 8 + h + 1) / 24.0f) * (float)dil * 1.4426950408889634f;
;     const float basel = -cb * (float)(128 + lq - 4 * gq);
.LBB0_430:
	s_cmp_lt_i32 s84, 5
	s_cselect_b64 s[2:3], -1, 0
	s_and_b64 s[0:1], s[2:3], s[0:1]
	s_andn2_b64 vcc, exec, s[0:1]
	s_cbranch_vccnz .LBB0_456
	v_writelane_b32 v239, s2, 63
	s_nop 0
	v_readlane_b32 s0, v239, 0
	s_cmpk_gt_i32 s0, 0x2ff
	v_writelane_b32 v238, s3, 0
	s_cbranch_scc1 .LBB0_455
	v_lshlrev_b32_e32 v5, 2, v154
	v_and_b32_e32 v119, 15, v154
	v_bfe_u32 v1, v154, 4, 2
	v_and_b32_e32 v6, 12, v5
	v_bfe_u32 v7, v154, 2, 2
	v_lshrrev_b32_e32 v2, 2, v154
	v_lshlrev_b32_e32 v4, 8, v119
	v_or_b32_e32 v8, v6, v7
	v_bitop3_b32 v6, v6, v1, v7 bitop3:0x36
	v_lshrrev_b32_e32 v122, 4, v154
	v_and_b32_e32 v2, 12, v2
	v_bfe_u32 v3, v154, 6, 2
	v_lshl_or_b32 v123, v6, 4, v4
	v_bitop3_b32 v6, v1, v8, 4 bitop3:0x36
	v_lshlrev_b32_e32 v0, 8, v122
	v_bitop3_b32 v2, v2, v119, v3 bitop3:0x36
	v_lshl_or_b32 v124, v6, 4, v4
	v_bitop3_b32 v6, v1, v8, 8 bitop3:0x36
	v_lshl_or_b32 v125, v6, 4, v4
	v_bitop3_b32 v6, v1, v8, 12 bitop3:0x36
	v_lshl_or_b32 v127, v2, 4, v0
	v_lshlrev_b32_e32 v2, 2, v1
	v_lshl_or_b32 v126, v6, 4, v4
	v_xor_b32_e32 v6, v1, v119
	v_lshl_or_b32 v123, v6, 4, v4
	v_or_b32_e32 v6, 4, v1
	v_xor_b32_e32 v6, v6, v119
	v_lshl_or_b32 v124, v6, 4, v4
	v_or_b32_e32 v6, 8, v1
	v_xor_b32_e32 v6, v6, v119
	v_lshl_or_b32 v125, v6, 4, v4
	v_or_b32_e32 v6, 12, v1
	v_xor_b32_e32 v6, v6, v119
	v_lshl_or_b32 v126, v6, 4, v4
	v_and_b32_e32 v6, 15, v122
	v_xor_b32_e32 v6, v6, v119
	v_lshl_or_b32 v127, v6, 4, v0
	v_or_b32_e32 v4, v2, v7
	v_lshlrev_b32_e32 v7, 1, v4
	v_and_b32_e32 v6, 1, v154
	v_and_b32_e32 v8, 14, v7
	v_and_b32_e32 v5, 8, v5
	v_lshl_or_b32 v4, v4, 8, v5
	v_or_b32_e32 v5, v8, v6
	v_lshl_or_b32 v128, v5, 4, v4
	v_or_b32_e32 v5, 2, v6
	v_bitop3_b32 v5, v7, v5, 14 bitop3:0x6c
	v_lshl_or_b32 v129, v5, 4, v4
	v_or_b32_e32 v5, 4, v6
	v_bitop3_b32 v5, v7, v5, 14 bitop3:0x6c
	v_lshrrev_b32_e32 v3, 3, v154
	v_lshl_or_b32 v130, v5, 4, v4
	v_or_b32_e32 v5, 6, v6
	v_bitop3_b32 v3, v3, v119, 14 bitop3:0x6c
	v_bitop3_b32 v5, v7, v5, 14 bitop3:0x6c
	v_lshlrev_b32_e32 v3, 4, v3
	v_lshl_or_b32 v131, v5, 4, v4
	v_or_b32_e32 v5, 8, v6
	s_mov_b32 s0, 0x10000
	v_bitop3_b32 v5, v7, v5, 14 bitop3:0x6c
	v_or3_b32 v136, v3, v0, s0
	v_or_b32_e32 v0, 0x80, v119
	v_lshl_or_b32 v132, v5, 4, v4
	v_or_b32_e32 v5, 10, v6
	v_sub_u32_e32 v0, v0, v2
	v_bitop3_b32 v5, v7, v5, 14 bitop3:0x6c
	v_cvt_f32_ubyte0_e32 v137, v0
	v_or_b32_e32 v0, 1, v2
	v_lshl_or_b32 v133, v5, 4, v4
	v_or_b32_e32 v5, 12, v6
	v_cmp_ge_u32_e64 s[4:5], v2, v119
	v_cmp_ge_u32_e64 s[6:7], v0, v119
	v_or_b32_e32 v0, 2, v2
	v_or_b32_e32 v3, 3, v2
	v_cmp_gt_u32_e64 s[12:13], v2, v119
	v_cmp_lt_u32_e64 s[14:15], v2, v119
	v_mbcnt_lo_u32_b32 v2, -1, 0
	v_bitop3_b32 v5, v7, v5, 14 bitop3:0x6c
	v_mbcnt_hi_u32_b32 v2, -1, v2
	v_lshl_or_b32 v134, v5, 4, v4
	v_bitop3_b32 v5, v7, v6, 14 bitop3:0x4e
	v_and_b32_e32 v6, 64, v2
	v_lshl_or_b32 v135, v5, 4, v4
	v_xor_b32_e32 v5, 16, v2
	v_add_u32_e32 v6, 64, v6
	v_cmp_lt_i32_e32 vcc, v5, v6
	v_cmp_ge_u32_e64 s[10:11], v3, v119
	v_cmp_gt_u32_e64 s[18:19], v3, v119
	v_cndmask_b32_e32 v5, v2, v5, vcc
	v_lshlrev_b32_e32 v139, 2, v5
	v_xor_b32_e32 v5, 32, v2
	v_cmp_lt_i32_e32 vcc, v5, v6
	v_mov_b32_e32 v3, 0
	s_mov_b64 s[0:1], 0x7c00000
	v_cndmask_b32_e32 v2, v2, v5, vcc
	v_lshlrev_b32_e32 v140, 2, v2
	v_lshlrev_b32_e32 v2, 4, v1
	v_lshl_add_u64 v[6:7], s[82:83], 0, v[2:3]
	v_cmp_ge_u32_e64 s[8:9], v0, v119
	v_cmp_gt_u32_e64 s[16:17], v0, v119
	v_lshlrev_b32_e32 v0, 3, v119
	v_lshlrev_b32_e32 v4, 3, v1
	v_lshl_add_u64 v[68:69], s[80:81], 0, v[2:3]
	v_lshl_add_u64 v[70:71], v[6:7], 0, s[0:1]
	v_lshlrev_b32_e32 v2, 4, v119
	v_readlane_b32 s0, v239, 0
	v_or_b32_e32 v138, 0xffffff80, v122
	s_mov_b32 s41, 0
	v_cmp_eq_u32_e64 s[2:3], 0, v1
	v_lshl_add_u64 v[72:73], s[82:83], 0, v[2:3]
	v_mov_b32_e32 v141, 0x42800000
	v_lshlrev_b32_e32 v74, 1, v4
	v_mov_b32_e32 v75, v3
	v_lshlrev_b32_e32 v76, 1, v0
	v_mov_b32_e32 v77, v3
	v_mov_b64_e32 v[78:79], 0x2d0000
	v_mov_b64_e32 v[80:81], 0x240000
	v_mov_b64_e32 v[82:83], 0x360000
	v_mov_b64_e32 v[84:85], 0x3f0000
	v_mov_b32_e32 v142, 0xff800000
	s_mov_b32 s25, s0
	s_branch .LBB0_434
